# dense attention items: blocks lb>=32 take their (A,B) item pairs in the opposite order, so co-resident blocks run different branch types
# baseline (speedup 1.0000x reference)
; DI int otid() { int t; asm volatile("v_mov_b32 %0, %1" : "=v"(t) : "v"((int)threadIdx.x)); __builtin_assume(t >= 0 && t < 256); return t; }
; DI void dense_item(const Params& p, int l, int combo, int qblk, char* smem, bool store) {
;   const int br = combo >> 4, bh = combo & 15, b = bh >> 2, h = bh & 3;
;   const size_t t0 = (size_t)b * SEQ + qblk * 128;
;   bf16_t* gate_io = P_PROJ + t0 * PW + C_GATE + br * 256 + h * 64;
;   float bbound = 0.f;
;   if (br != 0) {
;     const int ln = otid() & 63;
;     float gq = fabsf(p.gq_g[l * 64 + ln]), gk = fabsf(p.gk_g[l * 64 + ln]);
; #pragma unroll
;     for (int o = 32; o; o >>= 1) { gq = fmaxf(gq, __shfl_xor(gq, o)); gk = fmaxf(gk, __shfl_xor(gk, o)); }
;     bbound = 64.0f * QS64 * 1.02f * gq * gk + 0.05f;
;   }
;   if (br == 0)
; DI void run_phase(const Params& p, int ph, char* smem, bool never) {
;     ...
;       for (int w = lb; w < 256; w += nl) { const int k = w >> 6, ck = ((k & 1) << 1 | (k >> 1)) ^ 1; dense_item(p, l, xcd + 8 * ck, w & 63, smem, true); }
.LBB0_164:
	s_lshr_b32 s31, s29, 5
	s_and_b32 s31, s31, 1
	s_lshl_b32 s31, s31, 6
	s_xor_b32 s31, s31, s29
	s_lshr_b32 s0, s31, 5
	s_and_b32 s0, s0, 2
	s_ashr_i32 s1, s31, 7
	s_or_b32 s30, s0, s1
	s_lshl_b32 s0, s30, 3
	v_readlane_b32 s1, v253, 54
	s_or_b32 s1, s0, s1
	s_lshl_b32 s1, s1, 11
	s_and_b32 s1, s1, 0x6000
	s_xor_b32 s34, s1, 0x4000
	s_lshl_b32 s1, s31, 7
	s_and_b32 s1, s1, 0x1f80
	s_or_b32 s35, s34, s1
	s_mul_i32 s31, s35, 0x1300
	s_cmp_lt_u32 s0, 16
	s_mov_b64 s[0:1], -1
	s_cbranch_scc1 .LBB0_187
	v_mov_b32 v0, v188
	v_cmp_lt_i32_e32 vcc, v252, v189
	v_and_or_b32 v0, v0, 63, s28
	v_lshlrev_b32_e32 v0, 2, v0
	global_load_dword v2, v0, s[74:75]
	s_nop 0
	global_load_dword v0, v0, s[44:45]
	v_cndmask_b32_e32 v3, v204, v252, vcc
	v_lshlrev_b32_e32 v3, 2, v3
	v_cmp_lt_i32_e32 vcc, v191, v189
	s_lshl_b32 s0, s31, 1
	v_readlane_b32 s1, v253, 37
	v_cndmask_b32_e32 v4, v204, v191, vcc
	v_lshlrev_b32_e32 v4, 2, v4
	v_cmp_lt_i32_e32 vcc, v192, v189
	s_add_u32 s24, s1, s0
	v_readlane_b32 s0, v253, 38
	v_cndmask_b32_e32 v5, v204, v192, vcc
	v_lshlrev_b32_e32 v5, 2, v5
	v_cmp_lt_i32_e32 vcc, v193, v189
	s_mul_i32 s6, s34, 0x2600
	s_addc_u32 s25, s0, 0
	v_readlane_b32 s0, v255, 2
	s_add_u32 s22, s0, s6
	s_mov_b32 s0, 0x42700000
	s_waitcnt vmcnt(1)
	v_and_b32_e32 v6, 0x7fffffff, v2
	s_waitcnt vmcnt(0)
	v_and_b32_e32 v7, 0x7fffffff, v0
	ds_bpermute_b32 v6, v3, v6
	ds_bpermute_b32 v3, v3, v7
	v_max_f32_e64 v2, |v2|, |v2|
	v_max_f32_e64 v0, |v0|, |v0|
	s_waitcnt lgkmcnt(1)
	v_max_f32_e32 v6, v6, v6
	s_waitcnt lgkmcnt(0)
	v_max_f32_e32 v3, v3, v3
	v_max_f32_e32 v2, v2, v6
	v_max_f32_e32 v0, v0, v3
	ds_bpermute_b32 v3, v4, v2
	ds_bpermute_b32 v4, v4, v0
	v_cndmask_b32_e32 v6, v204, v193, vcc
	v_lshlrev_b32_e32 v6, 2, v6
	v_cmp_lt_i32_e32 vcc, v194, v189
	s_waitcnt lgkmcnt(1)
	v_max_f32_e32 v3, v3, v3
	s_waitcnt lgkmcnt(0)
	v_max_f32_e32 v4, v4, v4
	v_max_f32_e32 v2, v2, v3
	v_max_f32_e32 v0, v0, v4
	ds_bpermute_b32 v3, v5, v2
	ds_bpermute_b32 v4, v5, v0
	v_cndmask_b32_e32 v5, v204, v194, vcc
	v_lshlrev_b32_e32 v5, 2, v5
	v_cmp_lt_i32_e32 vcc, v195, v189
	s_waitcnt lgkmcnt(1)
	v_max_f32_e32 v3, v3, v3
	s_waitcnt lgkmcnt(0)
	v_max_f32_e32 v4, v4, v4
	v_max_f32_e32 v2, v2, v3
	v_max_f32_e32 v0, v0, v4
	ds_bpermute_b32 v3, v6, v2
	ds_bpermute_b32 v4, v6, v0
	v_cndmask_b32_e32 v6, v204, v195, vcc
	s_waitcnt lgkmcnt(1)
	v_max_f32_e32 v3, v3, v3
	s_waitcnt lgkmcnt(0)
	v_max_f32_e32 v4, v4, v4
	v_max_f32_e32 v2, v2, v3
	v_max_f32_e32 v0, v0, v4
	ds_bpermute_b32 v3, v5, v2
	ds_bpermute_b32 v4, v5, v0
	v_lshlrev_b32_e32 v5, 2, v6
	s_waitcnt lgkmcnt(1)
	v_max_f32_e32 v3, v3, v3
	s_waitcnt lgkmcnt(0)
	v_max_f32_e32 v4, v4, v4
	v_max_f32_e32 v2, v2, v3
	v_max_f32_e32 v0, v0, v4
	ds_bpermute_b32 v3, v5, v2
	ds_bpermute_b32 v4, v5, v0
	s_waitcnt lgkmcnt(1)
	v_max_f32_e32 v3, v3, v3
	s_waitcnt lgkmcnt(0)
	v_max_f32_e32 v4, v4, v4
	v_max_f32_e32 v2, v2, v3
	v_max_f32_e32 v0, v0, v4
	v_mul_f32_e32 v2, 0x413c5bb7, v2
	v_fmaak_f32 v35, v2, v0, 0x3d4ccccd
	v_cmp_ge_f32_e32 vcc, s0, v35
	v_readlane_b32 s0, v255, 5
	s_addc_u32 s23, s0, 0
	s_and_saveexec_b64 s[0:1], vcc
	s_xor_b64 s[0:1], exec, s[0:1]
	s_cbranch_execz .LBB0_169
; DI int otid() { int t; asm volatile("v_mov_b32 %0, %1" : "=v"(t) : "v"((int)threadIdx.x)); __builtin_assume(t >= 0 && t < 256); return t; }
; #define KLOAD() do { _Pragma("unroll") for (int i = 0; i < NKC; ++i) rk[i] = *(const u32x4*)(kp + i * 8); kp += kstep; } while (0)
; #define VLOAD() do { rv[0] = *(const u32x4*)vp0; rv[1] = *(const u32x4*)vp1; vp0 += vstep; vp1 += vstep; } while (0)
; #define KSTORE(st) do { _Pragma("unroll") for (int i = 0; i < NKC; ++i) *(u32x4*)(sKc + (st) * KBYTES + kso + i * 16) = rk[i]; } while (0)
; #define VSTORE(st) do { *(u32x4*)(sVc + (st) * VBYTES + vso) = rv[0]; *(u32x4*)(sVc + (st) * VBYTES + vso + 32 * VLD * 2) = rv[1]; } while (0)
; template <int DQK, bool FIXEDM>
; DI void attn_dense_mfma(const bf16_t* Qb, int ldq, const bf16_t* Kb, int ldk, const bf16_t* Vb, int ldv, bf16_t* gate_io, char* smem, bool store, float mbound) {
;     ...
;   const int tid = otid(), lane = tid & 63, wid = tid >> 6, r = lane & 31, h = lane >> 5;
;   bf16x8 qf[NS];
; #pragma unroll
;   for (int s = 0; s < NS; ++s) qf[s] = *(const bf16x8*)(Qb + (size_t)(wid * 32 + r) * ldq + 16 * s + 8 * h);
;   const bf16_t* kp = Kb + (size_t)(tid >> 2) * ldk + (tid & 3) * (NKC * 8);
;   const int kso = ((tid >> 2) * KLD + (tid & 3) * (NKC * 8)) * 2;
;   const bf16_t* vp0 = Vb + (size_t)(tid >> 3) * ldv + (tid & 7) * 8;
;   const bf16_t* vp1 = vp0 + (size_t)32 * ldv;
;   const int vso = ((tid >> 3) * VLD + (tid & 7) * 8) * 2;
;   const size_t kstep = (size_t)64 * ldk, vstep = (size_t)64 * ldv;
;   u32x4 rk[NKC], rv[2];
;     ...
;   const unsigned vb0 = (unsigned)(size_t)sVc + (unsigned)(((4 * h + ((lane & 15) >> 2)) * VLD + 16 * ((lane >> 4) & 1) + 4 * (lane & 3)) * 2);
;   f32x16 o0 = splat16(0.f), o1 = splat16(0.f), negm = splat16(FIXEDM ? -mbound : 0.f);
;   f32x16 pa0, pa1, pc0, pc1;
;   float m_run = 0.f, l_run = 0.f;
;   constexpr int NT = SEQ / 64;
;   __syncthreads();
;   KLOAD(); VLOAD(); KSTORE(0); VSTORE(0);
;   KLOAD(); KSTORE(1);
;   __syncthreads();
;   QKT(pa0, pa1, 0);
;   __syncthreads();
	s_movk_i32 s7, 0x60
	v_and_b32_e32 v197, 31, v188
	v_lshrrev_b32_e32 v0, 1, v188
	v_and_or_b32 v0, v0, s7, v197
	v_mul_u32_u24_e32 v162, 0x1300, v0
	v_mov_b32_e32 v163, 0
	v_bfe_u32 v198, v188, 5, 1
	v_lshlrev_b32_e32 v166, 2, v198
	v_lshlrev_b32_e32 v199, 1, v162
	v_lshl_add_u32 v199, v198, 4, v199
	global_load_dwordx4 v[114:117], v199, s[24:25] offset:0
	global_load_dwordx4 v[118:121], v199, s[24:25] offset:32
	global_load_dwordx4 v[122:125], v199, s[24:25] offset:64
	global_load_dwordx4 v[126:129], v199, s[24:25] offset:96
	v_lshrrev_b32_e32 v0, 2, v188
	v_and_b32_e32 v197, 3, v188
	s_movk_i32 s7, 0x2600
	v_mul_lo_u32 v164, v0, s7
	v_lshl_add_u32 v164, v197, 5, v164
	v_mul_u32_u24_e32 v167, 0x90, v0
	v_lshl_add_u32 v167, v197, 5, v167
	v_lshrrev_b32_e32 v0, 3, v188
	v_and_b32_e32 v197, 7, v188
	v_mul_lo_u32 v165, v0, s7
	v_lshl_add_u32 v165, v197, 4, v165
	v_mul_u32_u24_e32 v190, 0xc0, v0
	v_lshl_add_u32 v190, v197, 4, v190
	v_add_u32_e32 v190, 0x4800, v190
	v_and_b32_e32 v0, 31, v188
	v_mul_u32_u24_e32 v191, 0x90, v0
	v_lshl_add_u32 v191, v198, 4, v191
	v_bfe_u32 v0, v188, 2, 2
	v_lshl_add_u32 v0, v198, 2, v0
	v_mul_u32_u24_e32 v192, 0xc0, v0
	v_bfe_u32 v0, v188, 4, 1
	v_lshl_add_u32 v192, v0, 5, v192
	v_and_b32_e32 v0, 3, v188
	v_lshl_add_u32 v192, v0, 3, v192
	v_add_u32_e32 v192, 0x4800, v192
	s_mov_b32 s26, s22
	s_mov_b32 s27, s23
	s_mov_b32 s36, s22
	s_mov_b32 s37, s23
	s_add_u32 s4, s22, 0x4c000
	s_addc_u32 s5, s23, 0
	v_mov_b32_e32 v18, 0
	v_mov_b32_e32 v19, 0
	v_mov_b32_e32 v20, 0
	v_mov_b32_e32 v21, 0
	v_mov_b32_e32 v22, 0
	v_mov_b32_e32 v23, 0
	v_mov_b32_e32 v24, 0
	v_mov_b32_e32 v25, 0
	v_mov_b32_e32 v26, 0
	v_mov_b32_e32 v27, 0
	v_mov_b32_e32 v28, 0
	v_mov_b32_e32 v29, 0
	v_mov_b32_e32 v30, 0
	v_mov_b32_e32 v31, 0
	v_mov_b32_e32 v32, 0
	v_mov_b32_e32 v33, 0
	v_mov_b32_e32 v2, 0
	v_mov_b32_e32 v3, 0
	v_mov_b32_e32 v4, 0
	v_mov_b32_e32 v5, 0
	v_mov_b32_e32 v6, 0
	v_mov_b32_e32 v7, 0
	v_mov_b32_e32 v8, 0
	v_mov_b32_e32 v9, 0
	v_mov_b32_e32 v10, 0
	v_mov_b32_e32 v11, 0
	v_mov_b32_e32 v12, 0
	v_mov_b32_e32 v13, 0
	v_mov_b32_e32 v14, 0
	v_mov_b32_e32 v15, 0
	v_mov_b32_e32 v16, 0
	v_mov_b32_e32 v17, 0
	v_mov_b32_e32 v193, 0
	v_mov_b32_e32 v194, 0
	v_mov_b32_e32 v195, 0
	v_mov_b32_e32 v196, 0
	s_barrier
	global_load_dwordx4 v[168:171], v164, s[26:27] offset:512
	global_load_dwordx4 v[172:175], v164, s[26:27] offset:528
	s_add_u32 s26, s26, 0x98000
	s_addc_u32 s27, s27, 0
	global_load_dwordx4 v[176:179], v165, s[36:37] offset:768
	global_load_dwordx4 v[180:183], v165, s[4:5] offset:768
	s_add_u32 s36, s36, 0x98000
	s_addc_u32 s37, s37, 0
	s_add_u32 s4, s4, 0x98000
	s_addc_u32 s5, s5, 0
	s_waitcnt vmcnt(3)
	ds_write_b128 v167, v[168:171] offset:0
	s_waitcnt vmcnt(2)
	ds_write_b128 v167, v[172:175] offset:16
	s_waitcnt vmcnt(1)
	ds_write_b128 v190, v[176:179] offset:0
	s_waitcnt vmcnt(0)
	ds_write_b128 v190, v[180:183] offset:6144
	global_load_dwordx4 v[168:171], v164, s[26:27] offset:512
	global_load_dwordx4 v[172:175], v164, s[26:27] offset:528
	s_add_u32 s26, s26, 0x98000
	s_addc_u32 s27, s27, 0
	s_waitcnt vmcnt(1)
	ds_write_b128 v167, v[168:171] offset:9216
	s_waitcnt vmcnt(0)
	ds_write_b128 v167, v[172:175] offset:9232
	s_waitcnt lgkmcnt(0)
	s_barrier
	ds_read_b128 v[34:37], v191 offset:0
	ds_read_b128 v[38:41], v191 offset:32
	ds_read_b128 v[42:45], v191 offset:64
	ds_read_b128 v[46:49], v191 offset:96
	ds_read_b128 v[130:133], v191 offset:4608
	ds_read_b128 v[134:137], v191 offset:4640
	ds_read_b128 v[138:141], v191 offset:4672
	ds_read_b128 v[142:145], v191 offset:4704
	s_waitcnt lgkmcnt(7)
	v_mfma_f32_32x32x16_bf16 v[50:65], v[34:37], v[114:117], 0
	s_waitcnt lgkmcnt(6)
	v_mfma_f32_32x32x16_bf16 v[50:65], v[38:41], v[118:121], v[50:65]
	s_waitcnt lgkmcnt(5)
	v_mfma_f32_32x32x16_bf16 v[50:65], v[42:45], v[122:125], v[50:65]
	s_waitcnt lgkmcnt(4)
	v_mfma_f32_32x32x16_bf16 v[50:65], v[46:49], v[126:129], v[50:65]
	s_waitcnt lgkmcnt(3)
	v_mfma_f32_32x32x16_bf16 v[66:81], v[130:133], v[114:117], 0
	s_waitcnt lgkmcnt(2)
	v_mfma_f32_32x32x16_bf16 v[66:81], v[134:137], v[118:121], v[66:81]
	s_waitcnt lgkmcnt(1)
	v_mfma_f32_32x32x16_bf16 v[66:81], v[138:141], v[122:125], v[66:81]
	s_waitcnt lgkmcnt(0)
	v_mfma_f32_32x32x16_bf16 v[66:81], v[142:145], v[126:129], v[66:81]
	s_barrier
	s_mov_b32 s7, 0
